# attention PV: V-transpose fragment reads rotated through 3 spare register sets and issued ahead of the exp block, counted lgkmcnt, inline-asm nop pads removed
# speedup vs baseline: 1.0090x; 1.0037x over previous
.LBB0_319:
	v_or_b32_e32 v221, s31, v202
	v_mad_u32_u24 v225, v221, s89, v206
	ds_read_b64_tr_b16 v[226:227], v225 offset:18432
	ds_read_b64_tr_b16 v[228:229], v225 offset:19584
	ds_read_b64_tr_b16 v[230:231], v225 offset:18496
	ds_read_b64_tr_b16 v[232:233], v225 offset:19648
	ds_read_b64_tr_b16 v[234:235], v225 offset:20736
	ds_read_b64_tr_b16 v[236:237], v225 offset:21888
	v_pk_add_f32 v[114:115], v[114:115], v[186:187] op_sel_hi:[1,0] neg_lo:[0,1] neg_hi:[0,1]
	v_pk_add_f32 v[116:117], v[116:117], v[186:187] op_sel_hi:[1,0] neg_lo:[0,1] neg_hi:[0,1]
	v_exp_f32_e32 v190, v114
	v_exp_f32_e32 v191, v115
	v_exp_f32_e32 v192, v116
	v_exp_f32_e32 v193, v117
	v_pk_add_f32 v[116:117], v[118:119], v[186:187] op_sel_hi:[1,0] neg_lo:[0,1] neg_hi:[0,1]
	v_pk_add_f32 v[114:115], v[190:191], 0 op_sel_hi:[1,0]
	v_exp_f32_e32 v194, v116
	v_exp_f32_e32 v195, v117
	v_pk_add_f32 v[116:117], v[120:121], v[186:187] op_sel_hi:[1,0] neg_lo:[0,1] neg_hi:[0,1]
	v_pk_add_f32 v[114:115], v[192:193], v[114:115]
	v_exp_f32_e32 v196, v116
	v_exp_f32_e32 v197, v117
	v_pk_add_f32 v[116:117], v[122:123], v[186:187] op_sel_hi:[1,0] neg_lo:[0,1] neg_hi:[0,1]
	v_pk_add_f32 v[114:115], v[194:195], v[114:115]
	v_exp_f32_e32 v122, v116
	v_exp_f32_e32 v123, v117
	v_pk_add_f32 v[116:117], v[124:125], v[186:187] op_sel_hi:[1,0] neg_lo:[0,1] neg_hi:[0,1]
	v_pk_add_f32 v[114:115], v[196:197], v[114:115]
	v_exp_f32_e32 v124, v116
	v_exp_f32_e32 v125, v117
	v_pk_add_f32 v[116:117], v[126:127], v[186:187] op_sel_hi:[1,0] neg_lo:[0,1] neg_hi:[0,1]
	v_pk_add_f32 v[114:115], v[122:123], v[114:115]
	v_exp_f32_e32 v126, v116
	v_exp_f32_e32 v127, v117
	v_pk_add_f32 v[116:117], v[128:129], v[186:187] op_sel_hi:[1,0] neg_lo:[0,1] neg_hi:[0,1]
	v_pk_add_f32 v[114:115], v[124:125], v[114:115]
	v_exp_f32_e32 v128, v116
	v_exp_f32_e32 v129, v117
	v_pk_add_f32 v[114:115], v[126:127], v[114:115]
	v_pk_add_f32 v[98:99], v[98:99], v[186:187] op_sel_hi:[1,0] neg_lo:[0,1] neg_hi:[0,1]
	v_pk_add_f32 v[100:101], v[100:101], v[186:187] op_sel_hi:[1,0] neg_lo:[0,1] neg_hi:[0,1]
	v_pk_add_f32 v[116:117], v[128:129], v[114:115]
	v_exp_f32_e32 v114, v98
	v_exp_f32_e32 v115, v99
	v_pk_add_f32 v[82:83], v[82:83], v[188:189] op_sel_hi:[1,0] neg_lo:[0,1] neg_hi:[0,1]
	v_pk_add_f32 v[84:85], v[84:85], v[188:189] op_sel_hi:[1,0] neg_lo:[0,1] neg_hi:[0,1]
	v_pk_add_f32 v[66:67], v[66:67], v[188:189] op_sel_hi:[1,0] neg_lo:[0,1] neg_hi:[0,1]
	v_pk_add_f32 v[98:99], v[114:115], v[116:117]
	v_exp_f32_e32 v116, v100
	v_exp_f32_e32 v117, v101
	v_pk_add_f32 v[100:101], v[102:103], v[186:187] op_sel_hi:[1,0] neg_lo:[0,1] neg_hi:[0,1]
	v_pk_add_f32 v[68:69], v[68:69], v[188:189] op_sel_hi:[1,0] neg_lo:[0,1] neg_hi:[0,1]
	v_exp_f32_e32 v118, v100
	v_exp_f32_e32 v119, v101
	v_pk_add_f32 v[100:101], v[104:105], v[186:187] op_sel_hi:[1,0] neg_lo:[0,1] neg_hi:[0,1]
	v_pk_add_f32 v[98:99], v[116:117], v[98:99]
	v_exp_f32_e32 v120, v100
	v_exp_f32_e32 v121, v101
	v_pk_add_f32 v[98:99], v[118:119], v[98:99]
	v_or_b32_e32 v207, s31, v202
	v_pk_add_f32 v[100:101], v[120:121], v[98:99]
	v_pk_add_f32 v[98:99], v[106:107], v[186:187] op_sel_hi:[1,0] neg_lo:[0,1] neg_hi:[0,1]
	s_nop 0
	v_exp_f32_e32 v98, v98
	v_exp_f32_e32 v99, v99
	s_nop 0
	v_pk_add_f32 v[102:103], v[98:99], v[100:101]
	v_pk_add_f32 v[100:101], v[108:109], v[186:187] op_sel_hi:[1,0] neg_lo:[0,1] neg_hi:[0,1]
	v_exp_f32_e32 v108, v84
	v_exp_f32_e32 v100, v100
	v_exp_f32_e32 v101, v101
	v_exp_f32_e32 v109, v85
	v_pk_add_f32 v[84:85], v[86:87], v[188:189] op_sel_hi:[1,0] neg_lo:[0,1] neg_hi:[0,1]
	v_pk_add_f32 v[104:105], v[100:101], v[102:103]
	v_pk_add_f32 v[102:103], v[110:111], v[186:187] op_sel_hi:[1,0] neg_lo:[0,1] neg_hi:[0,1]
	v_exp_f32_e32 v110, v84
	v_exp_f32_e32 v102, v102
	v_exp_f32_e32 v103, v103
	v_exp_f32_e32 v111, v85
	v_pk_add_f32 v[84:85], v[88:89], v[188:189] op_sel_hi:[1,0] neg_lo:[0,1] neg_hi:[0,1]
	v_pk_add_f32 v[106:107], v[102:103], v[104:105]
	v_pk_add_f32 v[104:105], v[112:113], v[186:187] op_sel_hi:[1,0] neg_lo:[0,1] neg_hi:[0,1]
	v_exp_f32_e32 v112, v84
	v_exp_f32_e32 v104, v104
	v_exp_f32_e32 v105, v105
	v_exp_f32_e32 v113, v85
	v_pk_add_f32 v[84:85], v[90:91], v[188:189] op_sel_hi:[1,0] neg_lo:[0,1] neg_hi:[0,1]
	v_pk_add_f32 v[106:107], v[104:105], v[106:107]
	s_nop 0
	v_add_f32_e32 v106, v106, v107
	v_add_f32_e32 v201, v201, v106
	v_exp_f32_e32 v106, v82
	v_exp_f32_e32 v107, v83
	v_exp_f32_e32 v90, v84
	v_exp_f32_e32 v91, v85
	v_pk_add_f32 v[84:85], v[92:93], v[188:189] op_sel_hi:[1,0] neg_lo:[0,1] neg_hi:[0,1]
	v_pk_add_f32 v[82:83], v[106:107], 0 op_sel_hi:[1,0]
	v_exp_f32_e32 v92, v84
	v_pk_add_f32 v[82:83], v[108:109], v[82:83]
	v_exp_f32_e32 v93, v85
	v_pk_add_f32 v[84:85], v[94:95], v[188:189] op_sel_hi:[1,0] neg_lo:[0,1] neg_hi:[0,1]
	v_pk_add_f32 v[82:83], v[110:111], v[82:83]
	v_exp_f32_e32 v94, v84
	v_exp_f32_e32 v95, v85
	v_pk_add_f32 v[84:85], v[96:97], v[188:189] op_sel_hi:[1,0] neg_lo:[0,1] neg_hi:[0,1]
	v_pk_add_f32 v[82:83], v[112:113], v[82:83]
	v_exp_f32_e32 v96, v84
	v_exp_f32_e32 v97, v85
	v_pk_add_f32 v[82:83], v[90:91], v[82:83]
	s_nop 0
	v_pk_add_f32 v[82:83], v[92:93], v[82:83]
	s_nop 0
	v_pk_add_f32 v[82:83], v[94:95], v[82:83]
	s_nop 0
	v_pk_add_f32 v[84:85], v[96:97], v[82:83]
	v_exp_f32_e32 v82, v66
	v_exp_f32_e32 v83, v67
	s_nop 0
	v_pk_add_f32 v[66:67], v[82:83], v[84:85]
	v_exp_f32_e32 v84, v68
	v_exp_f32_e32 v85, v69
	v_pk_add_f32 v[68:69], v[70:71], v[188:189] op_sel_hi:[1,0] neg_lo:[0,1] neg_hi:[0,1]
	v_pk_add_f32 v[66:67], v[84:85], v[66:67]
	v_exp_f32_e32 v86, v68
	v_exp_f32_e32 v87, v69
	v_pk_add_f32 v[68:69], v[72:73], v[188:189] op_sel_hi:[1,0] neg_lo:[0,1] neg_hi:[0,1]
	v_pk_add_f32 v[66:67], v[86:87], v[66:67]
	v_exp_f32_e32 v88, v68
	v_exp_f32_e32 v89, v69
	s_nop 0
	v_pk_add_f32 v[68:69], v[88:89], v[66:67]
	v_pk_add_f32 v[66:67], v[74:75], v[188:189] op_sel_hi:[1,0] neg_lo:[0,1] neg_hi:[0,1]
	s_nop 0
	v_exp_f32_e32 v66, v66
	v_exp_f32_e32 v67, v67
	s_nop 0
	v_pk_add_f32 v[70:71], v[66:67], v[68:69]
	v_pk_add_f32 v[68:69], v[76:77], v[188:189] op_sel_hi:[1,0] neg_lo:[0,1] neg_hi:[0,1]
	s_nop 0
	v_exp_f32_e32 v68, v68
	v_exp_f32_e32 v69, v69
	s_nop 0
	v_pk_add_f32 v[72:73], v[68:69], v[70:71]
	v_pk_add_f32 v[70:71], v[78:79], v[188:189] op_sel_hi:[1,0] neg_lo:[0,1] neg_hi:[0,1]
	s_nop 0
	v_exp_f32_e32 v70, v70
	v_exp_f32_e32 v71, v71
	s_nop 0
	v_pk_add_f32 v[74:75], v[70:71], v[72:73]
	v_pk_add_f32 v[72:73], v[80:81], v[188:189] op_sel_hi:[1,0] neg_lo:[0,1] neg_hi:[0,1]
	s_nop 0
	v_exp_f32_e32 v72, v72
	v_exp_f32_e32 v73, v73
	s_nop 0
	v_pk_add_f32 v[74:75], v[72:73], v[74:75]
	s_nop 0
	v_add_f32_e32 v74, v74, v75
	v_add_f32_e32 v199, v199, v74
	v_cvt_pk_bf16_f32 v74, v190, v191
	v_cvt_pk_bf16_f32 v75, v192, v193
	v_cvt_pk_bf16_f32 v76, v194, v195
	v_cvt_pk_bf16_f32 v77, v196, v197
	v_cvt_pk_bf16_f32 v78, v106, v107
	v_cvt_pk_bf16_f32 v79, v108, v109
	v_cvt_pk_bf16_f32 v80, v110, v111
	v_cvt_pk_bf16_f32 v81, v112, v113
	s_waitcnt lgkmcnt(4)
	v_mfma_f32_32x32x16_bf16 v[50:65], v[226:229], v[74:77], v[50:65]
	v_mfma_f32_32x32x16_bf16 v[18:33], v[226:229], v[78:81], v[18:33]
	ds_read_b64_tr_b16 v[226:227], v225 offset:20800
	ds_read_b64_tr_b16 v[228:229], v225 offset:21952
	s_waitcnt lgkmcnt(4)
	v_mfma_f32_32x32x16_bf16 v[34:49], v[230:233], v[74:77], v[34:49]
	v_cvt_pk_bf16_f32 v74, v122, v123
	v_cvt_pk_bf16_f32 v75, v124, v125
	v_cvt_pk_bf16_f32 v76, v126, v127
	v_cvt_pk_bf16_f32 v77, v128, v129
	v_mfma_f32_32x32x16_bf16 v[2:17], v[230:233], v[78:81], v[2:17]
	v_cvt_pk_bf16_f32 v78, v90, v91
	v_cvt_pk_bf16_f32 v79, v92, v93
	v_cvt_pk_bf16_f32 v80, v94, v95
	v_cvt_pk_bf16_f32 v81, v96, v97
	ds_read_b64_tr_b16 v[230:231], v225 offset:23040
	ds_read_b64_tr_b16 v[232:233], v225 offset:24192
	s_waitcnt lgkmcnt(4)
	v_mfma_f32_32x32x16_bf16 v[50:65], v[234:237], v[74:77], v[50:65]
	v_mfma_f32_32x32x16_bf16 v[18:33], v[234:237], v[78:81], v[18:33]
	ds_read_b64_tr_b16 v[234:235], v225 offset:23104
	ds_read_b64_tr_b16 v[236:237], v225 offset:24256
	s_waitcnt lgkmcnt(4)
	v_mfma_f32_32x32x16_bf16 v[34:49], v[226:229], v[74:77], v[34:49]
	v_cvt_pk_bf16_f32 v74, v114, v115
	v_cvt_pk_bf16_f32 v75, v116, v117
	v_cvt_pk_bf16_f32 v76, v118, v119
	v_cvt_pk_bf16_f32 v77, v120, v121
	v_mfma_f32_32x32x16_bf16 v[2:17], v[226:229], v[78:81], v[2:17]
	v_cvt_pk_bf16_f32 v78, v82, v83
	v_cvt_pk_bf16_f32 v79, v84, v85
	v_cvt_pk_bf16_f32 v80, v86, v87
	v_cvt_pk_bf16_f32 v81, v88, v89
	ds_read_b64_tr_b16 v[226:227], v225 offset:25344
	ds_read_b64_tr_b16 v[228:229], v225 offset:26496
	s_waitcnt lgkmcnt(4)
	v_mfma_f32_32x32x16_bf16 v[50:65], v[230:233], v[74:77], v[50:65]
	v_mfma_f32_32x32x16_bf16 v[18:33], v[230:233], v[78:81], v[18:33]
	ds_read_b64_tr_b16 v[230:231], v225 offset:25408
	ds_read_b64_tr_b16 v[232:233], v225 offset:26560
	s_waitcnt lgkmcnt(4)
	v_mfma_f32_32x32x16_bf16 v[34:49], v[234:237], v[74:77], v[34:49]
	v_cvt_pk_bf16_f32 v74, v98, v99
	v_cvt_pk_bf16_f32 v75, v100, v101
	v_cvt_pk_bf16_f32 v76, v102, v103
	v_cvt_pk_bf16_f32 v77, v104, v105
	v_mfma_f32_32x32x16_bf16 v[2:17], v[234:237], v[78:81], v[2:17]
	v_cvt_pk_bf16_f32 v66, v66, v67
	v_cvt_pk_bf16_f32 v67, v68, v69
	v_cvt_pk_bf16_f32 v68, v70, v71
	v_cvt_pk_bf16_f32 v69, v72, v73
	s_waitcnt lgkmcnt(2)
	v_mfma_f32_32x32x16_bf16 v[50:65], v[226:229], v[74:77], v[50:65]
	v_mfma_f32_32x32x16_bf16 v[18:33], v[226:229], v[66:69], v[18:33]
	s_waitcnt lgkmcnt(0)
	v_mfma_f32_32x32x16_bf16 v[34:49], v[230:233], v[74:77], v[34:49]
	v_mfma_f32_32x32x16_bf16 v[2:17], v[230:233], v[66:69], v[2:17]

.LBB0_378:
	v_or_b32_e32 v221, s35, v215
	v_mad_u32_u24 v225, v221, s89, v224
	ds_read_b64_tr_b16 v[226:227], v225 offset:18432
	ds_read_b64_tr_b16 v[228:229], v225 offset:19584
	ds_read_b64_tr_b16 v[230:231], v225 offset:18496
	ds_read_b64_tr_b16 v[232:233], v225 offset:19648
	ds_read_b64_tr_b16 v[234:235], v225 offset:20736
	ds_read_b64_tr_b16 v[236:237], v225 offset:21888
	v_pk_add_f32 v[2:3], v[128:129], v[200:201] op_sel_hi:[1,0] neg_lo:[0,1] neg_hi:[0,1]
	v_pk_add_f32 v[4:5], v[130:131], v[200:201] op_sel_hi:[1,0] neg_lo:[0,1] neg_hi:[0,1]
	v_exp_f32_e32 v204, v2
	v_exp_f32_e32 v205, v3
	v_exp_f32_e32 v206, v4
	v_exp_f32_e32 v207, v5
	v_pk_add_f32 v[4:5], v[132:133], v[200:201] op_sel_hi:[1,0] neg_lo:[0,1] neg_hi:[0,1]
	v_pk_add_f32 v[2:3], v[204:205], 0 op_sel_hi:[1,0]
	v_exp_f32_e32 v208, v4
	v_exp_f32_e32 v209, v5
	v_pk_add_f32 v[4:5], v[134:135], v[200:201] op_sel_hi:[1,0] neg_lo:[0,1] neg_hi:[0,1]
	v_pk_add_f32 v[2:3], v[206:207], v[2:3]
	v_exp_f32_e32 v210, v4
	v_exp_f32_e32 v211, v5
	v_pk_add_f32 v[4:5], v[136:137], v[200:201] op_sel_hi:[1,0] neg_lo:[0,1] neg_hi:[0,1]
	v_pk_add_f32 v[2:3], v[208:209], v[2:3]
	v_exp_f32_e32 v128, v4
	v_exp_f32_e32 v129, v5
	v_pk_add_f32 v[4:5], v[138:139], v[200:201] op_sel_hi:[1,0] neg_lo:[0,1] neg_hi:[0,1]
	v_pk_add_f32 v[2:3], v[210:211], v[2:3]
	v_exp_f32_e32 v130, v4
	v_exp_f32_e32 v131, v5
	v_pk_add_f32 v[4:5], v[140:141], v[200:201] op_sel_hi:[1,0] neg_lo:[0,1] neg_hi:[0,1]
	v_pk_add_f32 v[2:3], v[128:129], v[2:3]
	v_exp_f32_e32 v132, v4
	v_exp_f32_e32 v133, v5
	v_pk_add_f32 v[4:5], v[142:143], v[200:201] op_sel_hi:[1,0] neg_lo:[0,1] neg_hi:[0,1]
	v_pk_add_f32 v[2:3], v[130:131], v[2:3]
	v_exp_f32_e32 v134, v4
	v_exp_f32_e32 v135, v5
	v_pk_add_f32 v[4:5], v[112:113], v[200:201] op_sel_hi:[1,0] neg_lo:[0,1] neg_hi:[0,1]
	v_pk_add_f32 v[2:3], v[132:133], v[2:3]
	v_exp_f32_e32 v10, v4
	v_exp_f32_e32 v11, v5
	v_pk_add_f32 v[4:5], v[114:115], v[200:201] op_sel_hi:[1,0] neg_lo:[0,1] neg_hi:[0,1]
	v_pk_add_f32 v[2:3], v[134:135], v[2:3]
	v_exp_f32_e32 v12, v4
	v_exp_f32_e32 v13, v5
	v_pk_add_f32 v[4:5], v[116:117], v[200:201] op_sel_hi:[1,0] neg_lo:[0,1] neg_hi:[0,1]
	v_pk_add_f32 v[2:3], v[10:11], v[2:3]
	v_exp_f32_e32 v14, v4
	v_exp_f32_e32 v15, v5
	v_pk_add_f32 v[4:5], v[118:119], v[200:201] op_sel_hi:[1,0] neg_lo:[0,1] neg_hi:[0,1]
	v_pk_add_f32 v[2:3], v[12:13], v[2:3]
	v_exp_f32_e32 v112, v4
	v_exp_f32_e32 v113, v5
	v_pk_add_f32 v[2:3], v[14:15], v[2:3]
	v_pk_add_f32 v[80:81], v[80:81], v[202:203] op_sel_hi:[1,0] neg_lo:[0,1] neg_hi:[0,1]
	v_pk_add_f32 v[82:83], v[82:83], v[202:203] op_sel_hi:[1,0] neg_lo:[0,1] neg_hi:[0,1]
	v_pk_add_f32 v[4:5], v[112:113], v[2:3]
	v_pk_add_f32 v[2:3], v[120:121], v[200:201] op_sel_hi:[1,0] neg_lo:[0,1] neg_hi:[0,1]
	s_nop 0
	v_exp_f32_e32 v2, v2
	v_exp_f32_e32 v3, v3
	s_nop 0
	v_pk_add_f32 v[6:7], v[2:3], v[4:5]
	v_pk_add_f32 v[4:5], v[122:123], v[200:201] op_sel_hi:[1,0] neg_lo:[0,1] neg_hi:[0,1]
	v_exp_f32_e32 v122, v80
	v_exp_f32_e32 v4, v4
	v_exp_f32_e32 v5, v5
	v_exp_f32_e32 v123, v81
	v_pk_add_f32 v[8:9], v[4:5], v[6:7]
	v_pk_add_f32 v[6:7], v[124:125], v[200:201] op_sel_hi:[1,0] neg_lo:[0,1] neg_hi:[0,1]
	v_exp_f32_e32 v124, v82
	v_exp_f32_e32 v6, v6
	v_exp_f32_e32 v7, v7
	v_exp_f32_e32 v125, v83
	v_pk_add_f32 v[82:83], v[84:85], v[202:203] op_sel_hi:[1,0] neg_lo:[0,1] neg_hi:[0,1]
	v_pk_add_f32 v[80:81], v[122:123], 0 op_sel_hi:[1,0]
	v_pk_add_f32 v[114:115], v[6:7], v[8:9]
	v_pk_add_f32 v[8:9], v[126:127], v[200:201] op_sel_hi:[1,0] neg_lo:[0,1] neg_hi:[0,1]
	v_exp_f32_e32 v126, v82
	v_exp_f32_e32 v8, v8
	v_exp_f32_e32 v9, v9
	v_exp_f32_e32 v127, v83
	v_pk_add_f32 v[82:83], v[86:87], v[202:203] op_sel_hi:[1,0] neg_lo:[0,1] neg_hi:[0,1]
	v_pk_add_f32 v[80:81], v[124:125], v[80:81]
	v_pk_add_f32 v[114:115], v[8:9], v[114:115]
	v_exp_f32_e32 v136, v82
	v_add_f32_e32 v114, v114, v115
	v_exp_f32_e32 v137, v83
	v_pk_add_f32 v[82:83], v[88:89], v[202:203] op_sel_hi:[1,0] neg_lo:[0,1] neg_hi:[0,1]
	v_add_f32_e32 v216, v216, v114
	v_exp_f32_e32 v114, v82
	v_exp_f32_e32 v115, v83
	v_pk_add_f32 v[82:83], v[90:91], v[202:203] op_sel_hi:[1,0] neg_lo:[0,1] neg_hi:[0,1]
	v_pk_add_f32 v[80:81], v[126:127], v[80:81]
	v_exp_f32_e32 v116, v82
	v_exp_f32_e32 v117, v83
	v_pk_add_f32 v[82:83], v[92:93], v[202:203] op_sel_hi:[1,0] neg_lo:[0,1] neg_hi:[0,1]
	v_pk_add_f32 v[80:81], v[136:137], v[80:81]
	v_exp_f32_e32 v118, v82
	v_exp_f32_e32 v119, v83
	v_pk_add_f32 v[82:83], v[94:95], v[202:203] op_sel_hi:[1,0] neg_lo:[0,1] neg_hi:[0,1]
	v_pk_add_f32 v[80:81], v[114:115], v[80:81]
	v_exp_f32_e32 v120, v82
	v_exp_f32_e32 v121, v83
	v_pk_add_f32 v[82:83], v[96:97], v[202:203] op_sel_hi:[1,0] neg_lo:[0,1] neg_hi:[0,1]
	v_pk_add_f32 v[80:81], v[116:117], v[80:81]
	v_exp_f32_e32 v88, v82
	v_exp_f32_e32 v89, v83
	v_pk_add_f32 v[82:83], v[98:99], v[202:203] op_sel_hi:[1,0] neg_lo:[0,1] neg_hi:[0,1]
	v_pk_add_f32 v[80:81], v[118:119], v[80:81]
	v_exp_f32_e32 v90, v82
	v_exp_f32_e32 v91, v83
	v_pk_add_f32 v[82:83], v[100:101], v[202:203] op_sel_hi:[1,0] neg_lo:[0,1] neg_hi:[0,1]
	v_pk_add_f32 v[80:81], v[120:121], v[80:81]
	v_exp_f32_e32 v92, v82
	v_exp_f32_e32 v93, v83
	v_pk_add_f32 v[82:83], v[102:103], v[202:203] op_sel_hi:[1,0] neg_lo:[0,1] neg_hi:[0,1]
	v_pk_add_f32 v[80:81], v[88:89], v[80:81]
	v_exp_f32_e32 v94, v82
	v_exp_f32_e32 v95, v83
	v_pk_add_f32 v[80:81], v[90:91], v[80:81]
	s_nop 0
	v_pk_add_f32 v[80:81], v[92:93], v[80:81]
	s_nop 0
	v_pk_add_f32 v[82:83], v[94:95], v[80:81]
	v_pk_add_f32 v[80:81], v[104:105], v[202:203] op_sel_hi:[1,0] neg_lo:[0,1] neg_hi:[0,1]
	v_or_b32_e32 v104, s35, v215
	v_exp_f32_e32 v80, v80
	v_exp_f32_e32 v81, v81
	s_nop 0
	v_pk_add_f32 v[84:85], v[80:81], v[82:83]
	v_pk_add_f32 v[82:83], v[106:107], v[202:203] op_sel_hi:[1,0] neg_lo:[0,1] neg_hi:[0,1]
	s_nop 0
	v_exp_f32_e32 v82, v82
	v_exp_f32_e32 v83, v83
	s_nop 0
	v_pk_add_f32 v[86:87], v[82:83], v[84:85]
	v_pk_add_f32 v[84:85], v[108:109], v[202:203] op_sel_hi:[1,0] neg_lo:[0,1] neg_hi:[0,1]
	v_exp_f32_e32 v84, v84
	v_exp_f32_e32 v85, v85
	s_nop 0
	v_pk_add_f32 v[96:97], v[84:85], v[86:87]
	v_pk_add_f32 v[86:87], v[110:111], v[202:203] op_sel_hi:[1,0] neg_lo:[0,1] neg_hi:[0,1]
	s_nop 0
	v_exp_f32_e32 v86, v86
	v_exp_f32_e32 v87, v87
	s_nop 0
	v_pk_add_f32 v[96:97], v[86:87], v[96:97]
	s_nop 0
	v_add_f32_e32 v96, v96, v97
	v_add_f32_e32 v212, v212, v96
	v_cvt_pk_bf16_f32 v96, v204, v205
	v_cvt_pk_bf16_f32 v97, v206, v207
	v_cvt_pk_bf16_f32 v98, v208, v209
	v_cvt_pk_bf16_f32 v99, v210, v211
	v_cvt_pk_bf16_f32 v100, v122, v123
	v_cvt_pk_bf16_f32 v101, v124, v125
	v_cvt_pk_bf16_f32 v102, v126, v127
	v_cvt_pk_bf16_f32 v103, v136, v137
	s_waitcnt lgkmcnt(4)
	v_mfma_f32_32x32x16_bf16 v[64:79], v[226:229], v[96:99], v[64:79]
	v_mfma_f32_32x32x16_bf16 v[32:47], v[226:229], v[100:103], v[32:47]
	ds_read_b64_tr_b16 v[226:227], v225 offset:20800
	ds_read_b64_tr_b16 v[228:229], v225 offset:21952
	s_waitcnt lgkmcnt(4)
	v_mfma_f32_32x32x16_bf16 v[48:63], v[230:233], v[96:99], v[48:63]
	v_cvt_pk_bf16_f32 v96, v128, v129
	v_cvt_pk_bf16_f32 v97, v130, v131
	v_cvt_pk_bf16_f32 v98, v132, v133
	v_cvt_pk_bf16_f32 v99, v134, v135
	v_mfma_f32_32x32x16_bf16 v[16:31], v[230:233], v[100:103], v[16:31]
	v_cvt_pk_bf16_f32 v100, v114, v115
	v_cvt_pk_bf16_f32 v101, v116, v117
	v_cvt_pk_bf16_f32 v102, v118, v119
	v_cvt_pk_bf16_f32 v103, v120, v121
	ds_read_b64_tr_b16 v[230:231], v225 offset:23040
	ds_read_b64_tr_b16 v[232:233], v225 offset:24192
	s_waitcnt lgkmcnt(4)
	v_mfma_f32_32x32x16_bf16 v[64:79], v[234:237], v[96:99], v[64:79]
	v_mfma_f32_32x32x16_bf16 v[32:47], v[234:237], v[100:103], v[32:47]
	ds_read_b64_tr_b16 v[234:235], v225 offset:23104
	ds_read_b64_tr_b16 v[236:237], v225 offset:24256
	s_waitcnt lgkmcnt(4)
	v_mfma_f32_32x32x16_bf16 v[48:63], v[226:229], v[96:99], v[48:63]
	v_cvt_pk_bf16_f32 v10, v10, v11
	v_cvt_pk_bf16_f32 v11, v12, v13
	v_cvt_pk_bf16_f32 v12, v14, v15
	v_cvt_pk_bf16_f32 v13, v112, v113
	v_mfma_f32_32x32x16_bf16 v[16:31], v[226:229], v[100:103], v[16:31]
	v_cvt_pk_bf16_f32 v88, v88, v89
	v_cvt_pk_bf16_f32 v89, v90, v91
	v_cvt_pk_bf16_f32 v90, v92, v93
	v_cvt_pk_bf16_f32 v91, v94, v95
	ds_read_b64_tr_b16 v[226:227], v225 offset:25344
	ds_read_b64_tr_b16 v[228:229], v225 offset:26496
	s_waitcnt lgkmcnt(4)
	v_mfma_f32_32x32x16_bf16 v[64:79], v[230:233], v[10:13], v[64:79]
	v_mfma_f32_32x32x16_bf16 v[32:47], v[230:233], v[88:91], v[32:47]
	ds_read_b64_tr_b16 v[230:231], v225 offset:25408
	ds_read_b64_tr_b16 v[232:233], v225 offset:26560
	s_waitcnt lgkmcnt(4)
	v_mfma_f32_32x32x16_bf16 v[48:63], v[234:237], v[10:13], v[48:63]
	v_cvt_pk_bf16_f32 v2, v2, v3
	v_cvt_pk_bf16_f32 v3, v4, v5
	v_cvt_pk_bf16_f32 v4, v6, v7
	v_cvt_pk_bf16_f32 v5, v8, v9
	v_mfma_f32_32x32x16_bf16 v[16:31], v[234:237], v[88:91], v[16:31]
	v_cvt_pk_bf16_f32 v6, v80, v81
	v_cvt_pk_bf16_f32 v7, v82, v83
	v_cvt_pk_bf16_f32 v8, v84, v85
	v_cvt_pk_bf16_f32 v9, v86, v87
	s_waitcnt lgkmcnt(2)
	v_mfma_f32_32x32x16_bf16 v[64:79], v[226:229], v[2:5], v[64:79]
	v_mfma_f32_32x32x16_bf16 v[32:47], v[226:229], v[6:9], v[32:47]
	s_waitcnt lgkmcnt(0)
	v_mfma_f32_32x32x16_bf16 v[48:63], v[230:233], v[2:5], v[48:63]
	v_mfma_f32_32x32x16_bf16 v[16:31], v[230:233], v[6:9], v[16:31]
